# nt on G1's unit stores (QD / o_intra / dS, consumed in G3)
# baseline (speedup 1.0000x reference)
.LBB0_1093:
	v_add_u32_e32 v129, 0, v127
	ds_read_b128 v[130:133], v129
	ds_read_b128 v[134:137], v129 offset:16
	ds_read_b128 v[138:141], v129 offset:32
	ds_read_b128 v[142:145], v129 offset:48
	v_add_u32_e32 v146, 0, v126
	s_waitcnt lgkmcnt(3)
	v_fma_f32 v130, v130, v98, v128
	v_fmac_f32_e32 v130, v131, v99
	v_fmac_f32_e32 v130, v132, v100
	v_fmac_f32_e32 v130, v133, v101
	s_waitcnt lgkmcnt(2)
	v_fmac_f32_e32 v130, v134, v102
	v_fmac_f32_e32 v130, v135, v103
	v_fmac_f32_e32 v130, v136, v104
	v_fmac_f32_e32 v130, v137, v105
	s_waitcnt lgkmcnt(1)
	v_fmac_f32_e32 v130, v138, v106
	v_fmac_f32_e32 v130, v139, v107
	v_fmac_f32_e32 v130, v140, v108
	v_fmac_f32_e32 v130, v141, v109
	s_waitcnt lgkmcnt(0)
	v_fmac_f32_e32 v130, v142, v110
	v_fmac_f32_e32 v130, v143, v111
	v_fmac_f32_e32 v130, v144, v112
	v_fmac_f32_e32 v130, v145, v113
	v_min_f32_e32 v131, 0, v130
	v_mul_f32_e64 v130, |v130|, s72
	v_exp_f32_e32 v130, v130
	v_add_u32_e32 v147, 0x10a00, v146
	v_add_u32_e32 v156, 0x10c04, v146
	v_add_u32_e32 v158, 0x10e08, v146
	v_add_f32_e32 v130, 1.0, v130
	s_add_i32 s9, s9, -4
	v_add_u32_e32 v126, 0x810, v126
	v_log_f32_e32 v130, v130
	s_nop 0
	v_add_u32_e32 v127, 0x100, v127
	v_add_u32_e32 v146, 0x1100c, v146
	v_mul_f32_e32 v133, 0x3f317217, v130
	v_fma_f32 v133, v130, s74, -v133
	v_fmac_f32_e32 v133, 0x3377d1cf, v130
	v_fmac_f32_e32 v133, 0x3f317217, v130
	s_cmp_eq_u32 s9, 0
	s_nop 0
	v_sub_f32_e32 v130, v131, v133
	v_fmac_f32_e32 v114, 0x3d800000, v130
	ds_write_b32 v147, v114
	ds_read_b128 v[130:133], v129 offset:64
	ds_read_b128 v[134:137], v129 offset:80
	ds_read_b128 v[138:141], v129 offset:96
	ds_read_b128 v[142:145], v129 offset:112
	s_waitcnt lgkmcnt(3)
	v_fma_f32 v130, v130, v98, v128
	v_fmac_f32_e32 v130, v131, v99
	v_fmac_f32_e32 v130, v132, v100
	v_fmac_f32_e32 v130, v133, v101
	s_waitcnt lgkmcnt(2)
	v_fmac_f32_e32 v130, v134, v102
	v_fmac_f32_e32 v130, v135, v103
	v_fmac_f32_e32 v130, v136, v104
	v_fmac_f32_e32 v130, v137, v105
	s_waitcnt lgkmcnt(1)
	v_fmac_f32_e32 v130, v138, v106
	v_fmac_f32_e32 v130, v139, v107
	v_fmac_f32_e32 v130, v140, v108
	v_fmac_f32_e32 v130, v141, v109
	s_waitcnt lgkmcnt(0)
	v_fmac_f32_e32 v130, v142, v110
	v_fmac_f32_e32 v130, v143, v111
	v_fmac_f32_e32 v130, v144, v112
	v_fmac_f32_e32 v130, v145, v113
	v_min_f32_e32 v131, 0, v130
	v_mul_f32_e64 v130, |v130|, s72
	v_exp_f32_e32 v130, v130
	s_nop 0
	v_add_f32_e32 v130, 1.0, v130
	s_nop 1
	v_log_f32_e32 v130, v130
	s_nop 0
	v_mul_f32_e32 v133, 0x3f317217, v130
	v_fma_f32 v133, v130, s74, -v133
	v_fmac_f32_e32 v133, 0x3377d1cf, v130
	v_fmac_f32_e32 v133, 0x3f317217, v130
	s_nop 1
	v_sub_f32_e32 v130, v131, v133
	v_fmac_f32_e32 v114, 0x3d800000, v130
	ds_write_b32 v156, v114
	ds_read_b128 v[130:133], v129 offset:128
	ds_read_b128 v[134:137], v129 offset:144
	ds_read_b128 v[138:141], v129 offset:160
	ds_read_b128 v[142:145], v129 offset:176
	s_waitcnt lgkmcnt(3)
	v_fma_f32 v130, v130, v98, v128
	v_fmac_f32_e32 v130, v131, v99
	v_fmac_f32_e32 v130, v132, v100
	v_fmac_f32_e32 v130, v133, v101
	s_waitcnt lgkmcnt(2)
	v_fmac_f32_e32 v130, v134, v102
	v_fmac_f32_e32 v130, v135, v103
	v_fmac_f32_e32 v130, v136, v104
	v_fmac_f32_e32 v130, v137, v105
	s_waitcnt lgkmcnt(1)
	v_fmac_f32_e32 v130, v138, v106
	v_fmac_f32_e32 v130, v139, v107
	v_fmac_f32_e32 v130, v140, v108
	v_fmac_f32_e32 v130, v141, v109
	s_waitcnt lgkmcnt(0)
	v_fmac_f32_e32 v130, v142, v110
	v_fmac_f32_e32 v130, v143, v111
	v_fmac_f32_e32 v130, v144, v112
	v_fmac_f32_e32 v130, v145, v113
	v_min_f32_e32 v131, 0, v130
	v_mul_f32_e64 v130, |v130|, s72
	v_exp_f32_e32 v130, v130
	s_nop 0
	v_add_f32_e32 v130, 1.0, v130
	s_nop 1
	v_log_f32_e32 v130, v130
	s_nop 0
	v_mul_f32_e32 v133, 0x3f317217, v130
	v_fma_f32 v133, v130, s74, -v133
	v_fmac_f32_e32 v133, 0x3377d1cf, v130
	v_fmac_f32_e32 v133, 0x3f317217, v130
	s_nop 1
	v_sub_f32_e32 v130, v131, v133
	v_fmac_f32_e32 v114, 0x3d800000, v130
	ds_write_b32 v158, v114
	ds_read_b128 v[130:133], v129 offset:192
	ds_read_b128 v[134:137], v129 offset:208
	ds_read_b128 v[138:141], v129 offset:224
	ds_read_b128 v[142:145], v129 offset:240
	s_waitcnt lgkmcnt(3)
	v_fma_f32 v129, v130, v98, v128
	v_fmac_f32_e32 v129, v131, v99
	v_fmac_f32_e32 v129, v132, v100
	v_fmac_f32_e32 v129, v133, v101
	s_waitcnt lgkmcnt(2)
	v_fmac_f32_e32 v129, v134, v102
	v_fmac_f32_e32 v129, v135, v103
	v_fmac_f32_e32 v129, v136, v104
	v_fmac_f32_e32 v129, v137, v105
	s_waitcnt lgkmcnt(1)
	v_fmac_f32_e32 v129, v138, v106
	v_fmac_f32_e32 v129, v139, v107
	v_fmac_f32_e32 v129, v140, v108
	v_fmac_f32_e32 v129, v141, v109
	s_waitcnt lgkmcnt(0)
	v_fmac_f32_e32 v129, v142, v110
	v_fmac_f32_e32 v129, v143, v111
	v_fmac_f32_e32 v129, v144, v112
	v_fmac_f32_e32 v129, v145, v113
	v_mul_f32_e64 v130, |v129|, s72
	v_exp_f32_e32 v130, v130
	v_min_f32_e32 v129, 0, v129
	v_add_f32_e32 v130, 1.0, v130
	s_nop 1
	v_log_f32_e32 v130, v130
	s_nop 0
	v_mul_f32_e32 v132, 0x3f317217, v130
	v_fma_f32 v132, v130, s74, -v132
	v_fmac_f32_e32 v132, 0x3377d1cf, v130
	v_fmac_f32_e32 v132, 0x3f317217, v130
	s_nop 1
	v_sub_f32_e32 v129, v129, v132
	v_fmac_f32_e32 v114, 0x3d800000, v129
	ds_write_b32 v146, v114
	s_cbranch_scc0 .LBB0_1093
	s_or_b32 s48, s8, s45
	v_bfe_u32 v158, v124, 5, 1
	s_ashr_i32 s50, s17, 6
	s_ashr_i32 s49, s48, 31
	v_lshl_or_b32 v160, s50, 1, v158
	s_lshl_b64 s[68:69], s[48:49], 4
	v_lshrrev_b32_e32 v98, 1, v124
	v_and_or_b32 v98, v98, 8, s68
	v_mov_b32_e32 v99, s69
	s_ashr_i32 s51, s50, 31
	v_lshlrev_b32_e32 v184, 5, v160
	v_lshl_add_u32 v159, v124, 2, s76
	v_lshl_add_u64 v[98:99], v[98:99], 0, s[50:51]
	v_add_u32_e32 v111, s76, v184
	ds_write_b32 v159, v114
	s_waitcnt lgkmcnt(0)
	s_barrier
	v_lshlrev_b64 v[102:103], 10, v[98:99]
	ds_read_b128 v[104:107], v111
	ds_read_b128 v[98:101], v111 offset:16
	ds_read_b128 v[128:131], v111 offset:512
	ds_read_b128 v[132:135], v111 offset:1024
	ds_read_b128 v[136:139], v111 offset:1536
	v_and_b32_e32 v156, 31, v124
	v_mul_u32_u24_e32 v110, 0x408, v156
	s_add_i32 s18, 0, 0x10a00
	v_cmp_gt_u32_e64 s[0:1], 8, v156
	s_waitcnt lgkmcnt(2)
	v_add_f32_e32 v126, v104, v128
	v_and_b32_e32 v108, 24, v124
	v_cndmask_b32_e64 v109, v104, 0, s[0:1]
	v_add3_u32 v104, s18, v110, v184
	ds_read2_b64 v[142:145], v104 offset1:1
	ds_read2_b64 v[178:181], v104 offset0:2 offset1:3
	v_cmp_lt_u32_e64 s[8:9], 15, v156
	v_cmp_eq_u32_e64 s[10:11], 24, v108
	s_waitcnt lgkmcnt(3)
	v_mov_b32_e32 v108, v132
	v_cndmask_b32_e64 v112, 0, v128, s[8:9]
	v_add_f32_e32 v109, v109, v112
	v_cndmask_b32_e64 v113, 0, v132, s[10:11]
	s_waitcnt lgkmcnt(2)
	v_mov_b32_e32 v112, v136
	v_pk_add_f32 v[108:109], v[108:109], v[112:113]
	s_waitcnt lgkmcnt(1)
	v_mov_b32_e32 v127, v142
	v_pk_add_f32 v[108:109], v[126:127], v[108:109]
	v_cndmask_b32_e64 v127, 0, v133, s[10:11]
	v_sub_f32_e32 v108, v108, v109
	v_mul_f32_e32 v108, 0x3fb8aa3b, v108
	v_mul_f32_e32 v104, 0x3fb8aa3b, v109
	v_mul_f32_e32 v110, 0xbfb8aa3b, v109
	v_exp_f32_e32 v128, v108
	v_cndmask_b32_e64 v108, v105, 0, s[0:1]
	v_cndmask_b32_e64 v109, 0, v129, s[8:9]
	v_add_f32_e32 v109, v108, v109
	v_mov_b32_e32 v108, v133
	v_mov_b32_e32 v126, v137
	v_add_f32_e32 v142, v105, v129
	v_pk_add_f32 v[108:109], v[108:109], v[126:127]
	s_waitcnt vmcnt(7)
	v_lshlrev_b32_e32 v126, 16, v94
	v_pk_add_f32 v[108:109], v[142:143], v[108:109]
	v_and_b32_e32 v127, 0xffff0000, v94
	v_mul_f32_e32 v94, 0xbfb8aa3b, v109
	v_exp_f32_e32 v112, v110
	v_mul_f32_e32 v105, 0x3fb8aa3b, v109
	v_exp_f32_e32 v113, v94
	v_exp_f32_e32 v104, v104
	v_exp_f32_e32 v105, v105
	s_waitcnt vmcnt(6)
	v_lshlrev_b32_e32 v140, 16, v90
	v_and_b32_e32 v141, 0xffff0000, v90
	v_sub_f32_e32 v90, v108, v109
	v_mul_f32_e32 v90, 0x3fb8aa3b, v90
	v_exp_f32_e32 v142, v90
	v_cndmask_b32_e64 v90, v106, 0, s[0:1]
	v_cndmask_b32_e64 v94, 0, v130, s[8:9]
	v_pk_mul_f32 v[182:183], v[112:113], v[140:141]
	v_add_f32_e32 v109, v90, v94
	v_cndmask_b32_e64 v113, 0, v134, s[10:11]
	v_mov_b32_e32 v108, v134
	v_mov_b32_e32 v112, v138
	v_pk_mul_f32 v[104:105], v[104:105], v[126:127]
	v_add_f32_e32 v126, v106, v130
	v_pk_add_f32 v[108:109], v[108:109], v[112:113]
	v_mov_b32_e32 v127, v144
	v_pk_add_f32 v[108:109], v[126:127], v[108:109]
	v_cndmask_b32_e64 v113, 0, v135, s[10:11]
	v_mul_f32_e32 v90, 0x3fb8aa3b, v109
	v_exp_f32_e32 v106, v90
	v_mul_f32_e32 v90, 0xbfb8aa3b, v109
	v_exp_f32_e32 v94, v90
	v_sub_f32_e32 v90, v108, v109
	v_mul_f32_e32 v90, 0x3fb8aa3b, v90
	v_exp_f32_e32 v126, v90
	v_cndmask_b32_e64 v90, v107, 0, s[0:1]
	v_cndmask_b32_e64 v108, 0, v131, s[8:9]
	v_add_f32_e32 v109, v90, v108
	v_mov_b32_e32 v108, v135
	v_mov_b32_e32 v112, v139
	v_add_f32_e32 v144, v107, v131
	v_pk_add_f32 v[108:109], v[108:109], v[112:113]
	ds_read_b128 v[166:169], v111 offset:528
	ds_read_b128 v[170:173], v111 offset:1040
	v_pk_add_f32 v[108:109], v[144:145], v[108:109]
	ds_read_b128 v[174:177], v111 offset:1552
	v_mul_f32_e32 v90, 0x3fb8aa3b, v109
	v_exp_f32_e32 v107, v90
	v_mul_f32_e32 v90, 0xbfb8aa3b, v109
	v_lshlrev_b32_e32 v112, 16, v95
	v_and_b32_e32 v113, 0xffff0000, v95
	v_exp_f32_e32 v95, v90
	v_sub_f32_e32 v90, v108, v109
	v_mul_f32_e32 v90, 0x3fb8aa3b, v90
	v_lshlrev_b32_e32 v134, 16, v91
	v_and_b32_e32 v135, 0xffff0000, v91
	v_exp_f32_e32 v138, v90
	v_cndmask_b32_e64 v90, v98, 0, s[0:1]
	s_waitcnt lgkmcnt(2)
	v_cndmask_b32_e64 v91, 0, v166, s[8:9]
	v_add_f32_e32 v91, v90, v91
	s_waitcnt lgkmcnt(1)
	v_cndmask_b32_e64 v109, 0, v170, s[10:11]
	v_mov_b32_e32 v90, v170
	s_waitcnt lgkmcnt(0)
	v_mov_b32_e32 v108, v174
	v_pk_mul_f32 v[106:107], v[106:107], v[112:113]
	v_add_f32_e32 v112, v98, v166
	v_pk_add_f32 v[90:91], v[90:91], v[108:109]
	v_mov_b32_e32 v113, v178
	v_pk_add_f32 v[90:91], v[112:113], v[90:91]
	v_cndmask_b32_e64 v131, 0, v171, s[10:11]
	v_sub_f32_e32 v90, v90, v91
	v_mul_f32_e32 v90, 0x3fb8aa3b, v90
	v_mul_f32_e32 v98, 0x3fb8aa3b, v91
	v_mul_f32_e32 v108, 0xbfb8aa3b, v91
	v_exp_f32_e32 v112, v90
	v_cndmask_b32_e64 v90, v99, 0, s[0:1]
	v_cndmask_b32_e64 v91, 0, v167, s[8:9]
	v_add_f32_e32 v91, v90, v91
	v_mov_b32_e32 v90, v171
	v_mov_b32_e32 v130, v175
	v_add_f32_e32 v178, v99, v167
	v_pk_add_f32 v[90:91], v[90:91], v[130:131]
	v_exp_f32_e32 v98, v98
	v_pk_add_f32 v[90:91], v[178:179], v[90:91]
	v_lshlrev_b32_e32 v130, 16, v96
	v_mul_f32_e32 v99, 0x3fb8aa3b, v91
	v_exp_f32_e32 v99, v99
	v_sub_f32_e32 v90, v90, v91
	v_mul_f32_e32 v90, 0x3fb8aa3b, v90
	v_and_b32_e32 v131, 0xffff0000, v96
	v_mul_f32_e32 v96, 0xbfb8aa3b, v91
	v_exp_f32_e32 v146, v90
	v_cndmask_b32_e64 v90, v100, 0, s[0:1]
	v_cndmask_b32_e64 v91, 0, v168, s[8:9]
	v_pk_mul_f32 v[98:99], v[98:99], v[130:131]
	v_add_f32_e32 v91, v90, v91
	v_cndmask_b32_e64 v131, 0, v172, s[10:11]
	v_mov_b32_e32 v90, v172
	v_mov_b32_e32 v130, v176
	v_add_f32_e32 v132, v100, v168
	v_pk_add_f32 v[90:91], v[90:91], v[130:131]
	v_mov_b32_e32 v133, v180
	v_pk_add_f32 v[90:91], v[132:133], v[90:91]
	v_lshlrev_b32_e32 v144, 16, v92
	v_sub_f32_e32 v90, v90, v91
	v_and_b32_e32 v145, 0xffff0000, v92
	v_mul_f32_e32 v92, 0x3fb8aa3b, v91
	v_mul_f32_e32 v90, 0x3fb8aa3b, v90
	v_exp_f32_e32 v100, v92
	v_mul_f32_e32 v92, 0xbfb8aa3b, v91
	v_exp_f32_e32 v110, v90
	v_cndmask_b32_e64 v90, v101, 0, s[0:1]
	v_cndmask_b32_e64 v91, 0, v169, s[8:9]
	v_add_f32_e32 v91, v90, v91
	v_cndmask_b32_e64 v131, 0, v173, s[10:11]
	v_mov_b32_e32 v90, v173
	v_mov_b32_e32 v130, v177
	v_add_f32_e32 v180, v101, v169
	v_pk_add_f32 v[90:91], v[90:91], v[130:131]
	v_exp_f32_e32 v109, v96
	v_pk_add_f32 v[90:91], v[180:181], v[90:91]
	v_exp_f32_e32 v96, v92
	v_mul_f32_e32 v92, 0x3fb8aa3b, v91
	v_exp_f32_e32 v101, v92
	v_mul_f32_e32 v92, 0xbfb8aa3b, v91
	v_exp_f32_e32 v108, v108
	v_lshlrev_b32_e32 v130, 16, v97
	v_and_b32_e32 v131, 0xffff0000, v97
	v_exp_f32_e32 v97, v92
	v_lshlrev_b32_e32 v147, 1, v156
	v_and_b32_e32 v165, 32, v124
	v_sub_f32_e32 v90, v90, v91
	v_cvt_pk_bf16_f32 v92, v98, v99
	v_and_or_b32 v98, v147, 30, v165
	v_lshl_add_u32 v164, v160, 4, 0
	v_pk_mul_f32 v[100:101], v[100:101], v[130:131]
	v_lshlrev_b32_e32 v130, 16, v93
	v_and_b32_e32 v131, 0xffff0000, v93
	v_mul_f32_e32 v90, 0x3fb8aa3b, v90
	v_lshl_add_u64 v[132:133], s[56:57], 0, v[102:103]
	v_lshlrev_b32_e32 v114, 4, v98
	v_pk_mul_f32 v[94:95], v[94:95], v[134:135]
	v_pk_mul_f32 v[108:109], v[108:109], v[144:145]
	v_pk_mul_f32 v[96:97], v[96:97], v[130:131]
	v_exp_f32_e32 v136, v90
	v_cvt_pk_bf16_f32 v90, v104, v105
	v_cvt_pk_bf16_f32 v91, v106, v107
	v_cvt_pk_bf16_f32 v93, v100, v101
	v_mad_u32_u24 v100, v156, s83, v164
	v_lshl_add_u64 v[98:99], v[132:133], 0, v[114:115]
	ds_write_b128 v100, v[90:93]
	global_store_dwordx4 v[98:99], v[90:93], off sc1 nt
	v_or_b32_e32 v114, 1, v147
	v_mul_u32_u24_e32 v113, 0x204, v114
	v_cvt_pk_bf16_f32 v90, v182, v183
	v_cvt_pk_bf16_f32 v91, v94, v95
	v_cvt_pk_bf16_f32 v92, v108, v109
	v_cvt_pk_bf16_f32 v93, v96, v97
	ds_write_b128 v100, v[90:93] offset:17408
	ds_read_b128 v[94:97], v111
	ds_read_b128 v[90:93], v111 offset:16
	ds_read_b128 v[98:101], v111 offset:512
	ds_read_b128 v[102:105], v111 offset:1024
	ds_read_b128 v[106:109], v111 offset:1536
	s_waitcnt lgkmcnt(4)
	v_cndmask_b32_e64 v127, v94, 0, s[0:1]
	ds_read_b128 v[166:169], v111 offset:528
	s_waitcnt lgkmcnt(3)
	v_add_f32_e32 v182, v94, v98
	v_add3_u32 v94, s18, v113, v184
	ds_read2_b32 v[184:185], v94 offset1:1
	v_cndmask_b32_e64 v129, 0, v98, s[8:9]
	v_add_f32_e32 v179, v127, v129
	s_waitcnt lgkmcnt(3)
	v_cndmask_b32_e64 v181, 0, v102, s[10:11]
	v_mov_b32_e32 v178, v102
	s_waitcnt lgkmcnt(2)
	v_mov_b32_e32 v180, v106
	v_pk_add_f32 v[178:179], v[178:179], v[180:181]
	s_waitcnt lgkmcnt(0)
	v_mov_b32_e32 v183, v184
	v_pk_add_f32 v[178:179], v[182:183], v[178:179]
	v_cndmask_b32_e64 v106, 0, v99, s[8:9]
	v_sub_f32_e32 v102, v178, v179
	v_mul_f32_e32 v102, 0x3fb8aa3b, v102
	v_exp_f32_e32 v129, v102
	v_cndmask_b32_e64 v102, v95, 0, s[0:1]
	ds_read_b128 v[170:173], v111 offset:1040
	ds_read_b128 v[174:177], v111 offset:1552
	ds_read2_b32 v[180:181], v94 offset0:2 offset1:3
	ds_read2_b32 v[186:187], v94 offset0:4 offset1:5
	ds_read2_b32 v[188:189], v94 offset0:6 offset1:7
	v_mul_f32_e32 v94, 0x3fb8aa3b, v179
	v_mul_f32_e32 v98, 0xbfb8aa3b, v179
	v_add_f32_e32 v179, v102, v106
	v_cndmask_b32_e64 v183, 0, v103, s[10:11]
	v_mov_b32_e32 v178, v103
	v_mov_b32_e32 v182, v107
	v_add_f32_e32 v184, v95, v99
	v_pk_add_f32 v[102:103], v[178:179], v[182:183]
	v_exp_f32_e32 v94, v94
	v_pk_add_f32 v[102:103], v[184:185], v[102:103]
	s_waitcnt vmcnt(6)
	v_lshlrev_b32_e32 v106, 16, v86
	v_mul_f32_e32 v95, 0x3fb8aa3b, v103
	v_exp_f32_e32 v95, v95
	v_and_b32_e32 v107, 0xffff0000, v86
	v_mul_f32_e32 v86, 0xbfb8aa3b, v103
	v_exp_f32_e32 v98, v98
	v_pk_mul_f32 v[94:95], v[94:95], v[106:107]
	s_waitcnt vmcnt(5)
	v_lshlrev_b32_e32 v106, 16, v82
	v_and_b32_e32 v107, 0xffff0000, v82
	v_sub_f32_e32 v82, v102, v103
	v_exp_f32_e32 v99, v86
	v_mul_f32_e32 v82, 0x3fb8aa3b, v82
	v_exp_f32_e32 v143, v82
	v_mov_b32_e32 v178, v140
	v_mov_b32_e32 v179, v106
	v_cndmask_b32_e64 v82, v96, 0, s[0:1]
	v_cndmask_b32_e64 v86, 0, v100, s[8:9]
	v_pk_mul_f32 v[98:99], v[98:99], v[106:107]
	v_pk_mul_f32 v[102:103], v[128:129], v[178:179]
	v_mov_b32_e32 v106, v141
	v_add_f32_e32 v129, v82, v86
	v_cndmask_b32_e64 v141, 0, v104, s[10:11]
	v_mov_b32_e32 v128, v104
	v_mov_b32_e32 v140, v108
	v_pk_mul_f32 v[106:107], v[142:143], v[106:107]
	v_add_f32_e32 v142, v96, v100
	v_pk_add_f32 v[128:129], v[128:129], v[140:141]
	s_waitcnt lgkmcnt(2)
	v_mov_b32_e32 v143, v180
	v_pk_add_f32 v[128:129], v[142:143], v[128:129]
	v_cndmask_b32_e64 v100, 0, v101, s[8:9]
	v_mul_f32_e32 v82, 0x3fb8aa3b, v129
	v_exp_f32_e32 v96, v82
	v_mul_f32_e32 v82, 0xbfb8aa3b, v129
	v_exp_f32_e32 v86, v82
	v_sub_f32_e32 v82, v128, v129
	v_mul_f32_e32 v82, 0x3fb8aa3b, v82
	v_exp_f32_e32 v127, v82
	v_cndmask_b32_e64 v82, v97, 0, s[0:1]
	v_add_f32_e32 v129, v82, v100
	v_cndmask_b32_e64 v141, 0, v105, s[10:11]
	v_mov_b32_e32 v128, v105
	v_mov_b32_e32 v140, v109
	v_add_f32_e32 v180, v97, v101
	v_pk_add_f32 v[100:101], v[128:129], v[140:141]
	v_lshlrev_b32_e32 v104, 16, v87
	v_pk_add_f32 v[100:101], v[180:181], v[100:101]
	v_and_b32_e32 v105, 0xffff0000, v87
	v_mul_f32_e32 v82, 0x3fb8aa3b, v101
	v_exp_f32_e32 v97, v82
	v_mul_f32_e32 v82, 0xbfb8aa3b, v101
	v_sub_f32_e32 v100, v100, v101
	v_exp_f32_e32 v87, v82
	v_mul_f32_e32 v100, 0x3fb8aa3b, v100
	v_exp_f32_e32 v139, v100
	v_lshlrev_b32_e32 v82, 16, v83
	v_and_b32_e32 v83, 0xffff0000, v83
	v_pk_mul_f32 v[96:97], v[96:97], v[104:105]
	v_pk_mul_f32 v[86:87], v[86:87], v[82:83]
	v_mov_b32_e32 v104, v134
	v_mov_b32_e32 v105, v82
	v_mov_b32_e32 v82, v135
	v_pk_mul_f32 v[100:101], v[126:127], v[104:105]
	v_pk_mul_f32 v[104:105], v[138:139], v[82:83]
	v_cndmask_b32_e64 v82, v90, 0, s[0:1]
	v_cndmask_b32_e64 v83, 0, v166, s[8:9]
	v_add_f32_e32 v83, v82, v83
	v_cndmask_b32_e64 v109, 0, v170, s[10:11]
	v_mov_b32_e32 v82, v170
	v_mov_b32_e32 v108, v174
	v_add_f32_e32 v126, v90, v166
	v_pk_add_f32 v[82:83], v[82:83], v[108:109]
	s_waitcnt lgkmcnt(1)
	v_mov_b32_e32 v127, v186
	v_pk_add_f32 v[82:83], v[126:127], v[82:83]
	v_cndmask_b32_e64 v127, 0, v171, s[10:11]
	v_sub_f32_e32 v82, v82, v83
	v_mul_f32_e32 v82, 0x3fb8aa3b, v82
	v_mul_f32_e32 v90, 0x3fb8aa3b, v83
	v_mul_f32_e32 v108, 0xbfb8aa3b, v83
	v_exp_f32_e32 v113, v82
	v_cndmask_b32_e64 v82, v91, 0, s[0:1]
	v_cndmask_b32_e64 v83, 0, v167, s[8:9]
	v_add_f32_e32 v83, v82, v83
	v_mov_b32_e32 v82, v171
	v_mov_b32_e32 v126, v175
	v_add_f32_e32 v186, v91, v167
	v_pk_add_f32 v[82:83], v[82:83], v[126:127]
	v_exp_f32_e32 v90, v90
	v_pk_add_f32 v[82:83], v[186:187], v[82:83]
	v_lshlrev_b32_e32 v126, 16, v88
	v_mul_f32_e32 v91, 0x3fb8aa3b, v83
	v_exp_f32_e32 v91, v91
	v_and_b32_e32 v127, 0xffff0000, v88
	v_sub_f32_e32 v82, v82, v83
	v_mul_f32_e32 v82, 0x3fb8aa3b, v82
	v_pk_mul_f32 v[90:91], v[90:91], v[126:127]
	v_lshlrev_b32_e32 v126, 16, v84
	v_and_b32_e32 v161, 50, v147
	v_mul_f32_e32 v88, 0xbfb8aa3b, v83
	v_mov_b32_e32 v128, v144
	v_exp_f32_e32 v147, v82
	v_mov_b32_e32 v129, v126
	v_cndmask_b32_e64 v82, v92, 0, s[0:1]
	v_cndmask_b32_e64 v83, 0, v168, s[8:9]
	v_pk_mul_f32 v[112:113], v[112:113], v[128:129]
	v_add_f32_e32 v83, v82, v83
	v_cndmask_b32_e64 v129, 0, v172, s[10:11]
	v_mov_b32_e32 v82, v172
	v_mov_b32_e32 v128, v176
	v_add_f32_e32 v134, v92, v168
	v_pk_add_f32 v[82:83], v[82:83], v[128:129]
	s_waitcnt lgkmcnt(0)
	v_mov_b32_e32 v135, v188
	v_pk_add_f32 v[82:83], v[134:135], v[82:83]
	v_and_b32_e32 v127, 0xffff0000, v84
	v_sub_f32_e32 v82, v82, v83
	v_mul_f32_e32 v84, 0x3fb8aa3b, v83
	v_mul_f32_e32 v82, 0x3fb8aa3b, v82
	v_exp_f32_e32 v92, v84
	v_mul_f32_e32 v84, 0xbfb8aa3b, v83
	v_exp_f32_e32 v111, v82
	v_cndmask_b32_e64 v82, v93, 0, s[0:1]
	v_cndmask_b32_e64 v83, 0, v169, s[8:9]
	v_add_f32_e32 v83, v82, v83
	v_cndmask_b32_e64 v129, 0, v173, s[10:11]
	v_mov_b32_e32 v82, v173
	v_mov_b32_e32 v128, v177
	v_add_f32_e32 v188, v93, v169
	v_pk_add_f32 v[82:83], v[82:83], v[128:129]
	v_exp_f32_e32 v109, v88
	v_pk_add_f32 v[82:83], v[188:189], v[82:83]
	v_exp_f32_e32 v88, v84
	v_mul_f32_e32 v84, 0x3fb8aa3b, v83
	v_exp_f32_e32 v93, v84
	v_mul_f32_e32 v84, 0xbfb8aa3b, v83
	v_sub_f32_e32 v82, v82, v83
	v_lshlrev_b32_e32 v128, 16, v89
	v_and_b32_e32 v129, 0xffff0000, v89
	v_exp_f32_e32 v89, v84
	v_mul_f32_e32 v82, 0x3fb8aa3b, v82
	v_exp_f32_e32 v137, v82
	v_exp_f32_e32 v108, v108
	v_lshlrev_b32_e32 v84, 16, v85
	v_and_b32_e32 v85, 0xffff0000, v85
	v_pk_mul_f32 v[92:93], v[92:93], v[128:129]
	v_pk_mul_f32 v[88:89], v[88:89], v[84:85]
	v_mov_b32_e32 v128, v130
	v_mov_b32_e32 v129, v84
	v_mov_b32_e32 v84, v131
	v_pk_mul_f32 v[110:111], v[110:111], v[128:129]
	v_pk_mul_f32 v[128:129], v[136:137], v[84:85]
	v_cvt_pk_bf16_f32 v84, v90, v91
	v_and_or_b32 v90, v114, 31, v165
	v_cvt_pk_bf16_f32 v85, v92, v93
	v_mad_u32_u24 v92, v114, s84, v164
	v_lshlrev_b32_e32 v114, 4, v90
	v_pk_mul_f32 v[108:109], v[108:109], v[126:127]
	v_cvt_pk_bf16_f32 v82, v94, v95
	v_cvt_pk_bf16_f32 v83, v96, v97
	v_lshl_add_u64 v[90:91], v[132:133], 0, v[114:115]
	v_lshlrev_b32_e32 v162, 2, v124
	ds_write_b128 v92, v[82:85]
	global_store_dwordx4 v[90:91], v[82:85], off sc1 nt
	v_and_b32_e32 v163, 4, v124
	v_mov_b32_e32 v126, v145
	v_cvt_pk_bf16_f32 v82, v98, v99
	v_cvt_pk_bf16_f32 v83, v86, v87
	v_cvt_pk_bf16_f32 v84, v108, v109
	v_cvt_pk_bf16_f32 v85, v88, v89
	ds_write_b128 v92, v[82:85] offset:17408
	v_and_b32_e32 v82, 8, v162
	v_or3_b32 v82, v161, v163, v82
	v_lshlrev_b32_e32 v82, 1, v82
	v_mul_lo_u32 v83, v160, s85
	v_add3_u32 v85, 0, v82, v83
	v_cvt_pk_bf16_f32 v84, v102, v103
	v_cvt_pk_bf16_f32 v86, v106, v107
	v_add_u32_e32 v85, 0x8800, v85
	v_pk_mul_f32 v[126:127], v[146:147], v[126:127]
	ds_write2_b32 v85, v84, v86 offset1:36
	v_cvt_pk_bf16_f32 v84, v100, v101
	v_cvt_pk_bf16_f32 v86, v104, v105
	ds_write2_b32 v85, v84, v86 offset0:72 offset1:108
	v_cvt_pk_bf16_f32 v84, v112, v113
	v_cvt_pk_bf16_f32 v86, v126, v127
	ds_write2_b32 v85, v84, v86 offset0:144 offset1:180
	v_cvt_pk_bf16_f32 v84, v110, v111
	v_cvt_pk_bf16_f32 v86, v128, v129
	ds_write2_b32 v85, v84, v86 offset0:216 offset1:252
	s_and_saveexec_b64 s[0:1], vcc
	s_cbranch_execz .LBB0_1096
	ds_read2st64_b32 v[84:85], v159 offset1:2
	ds_read2st64_b32 v[86:87], v159 offset0:4 offset1:6
	s_lshl_b64 s[8:9], s[48:49], 9
	s_add_u32 s8, s79, s8
	s_addc_u32 s9, s80, s9
	s_waitcnt lgkmcnt(1)
	v_mov_b32_e32 v88, v84
	s_waitcnt lgkmcnt(0)
	v_mov_b32_e32 v89, v86
	v_mov_b32_e32 v86, v85
	v_pk_add_f32 v[84:85], v[88:89], v[86:87]
	s_nop 0
	v_add_f32_e32 v84, v84, v85
	v_mul_f32_e32 v84, 0x3fb8aa3b, v84
	v_exp_f32_e32 v86, v84
	v_lshl_add_u64 v[84:85], v[124:125], 2, s[8:9]
	global_store_dword v[84:85], v148, off nt
	v_add_u32_e32 v84, 0x18b00, v157
	v_mul_f32_e32 v148, v148, v86
	ds_write_b32 v84, v86

.LBB0_1257:
	s_lshl_b32 s9, s88, 3
	s_or_b32 s68, s68, s9
	s_ashr_i32 s9, s8, 31
	v_and_b32_e32 v82, 63, v124
	s_add_u32 s8, s68, s8
	v_lshlrev_b32_e32 v114, 2, v82
	s_addc_u32 s9, s69, s9
	v_lshl_add_u64 v[124:125], s[12:13], 0, v[114:115]
	s_lshl_b64 s[8:9], s[8:9], 11
	v_lshl_add_u64 v[130:131], v[124:125], 0, s[8:9]
	s_nop 1
	v_cvt_pk_bf16_f32 v66, v66, v67
	s_or_b32 s10, s50, 1
	global_store_dword v[130:131], v66, off nt
	v_lshl_or_b32 v66, s10, 5, v156
	v_mul_lo_u32 v66, v66, s86
	v_add_u32_e32 v66, v128, v66
	ds_read_b128 v[82:85], v66 offset:53248
	v_cvt_pk_bf16_f32 v67, v68, v69
	global_store_dword v[130:131], v67, off offset:256 nt
	v_cvt_pk_bf16_f32 v67, v70, v71
	ds_read_b128 v[68:71], v66 offset:53280
	s_waitcnt lgkmcnt(1)
	v_mfma_f32_32x32x16_bf16 v[82:97], v[82:85], v[98:101], 0
	global_store_dword v[130:131], v67, off offset:512 nt
	v_cvt_pk_bf16_f32 v67, v72, v73
	global_store_dword v[130:131], v67, off offset:768 nt
	v_cvt_pk_bf16_f32 v67, v74, v75
	global_store_dword v[130:131], v67, off offset:1024 nt
	v_cvt_pk_bf16_f32 v67, v76, v77
	global_store_dword v[130:131], v67, off offset:1280 nt
	s_waitcnt lgkmcnt(0)
	v_mfma_f32_32x32x16_bf16 v[82:97], v[68:71], v[106:109], v[82:97]
	v_cvt_pk_bf16_f32 v67, v78, v79
	global_store_dword v[130:131], v67, off offset:1536 nt
	v_cvt_pk_bf16_f32 v67, v80, v81
	s_and_b64 vcc, exec, s[0:1]
	global_store_dword v[130:131], v67, off offset:1792 nt
	s_cbranch_vccnz .LBB0_1259
	ds_read_b128 v[68:71], v66 offset:53312
	ds_read_b128 v[72:75], v66 offset:53344
	s_waitcnt lgkmcnt(1)
	v_mfma_f32_32x32x16_bf16 v[82:97], v[68:71], v[102:105], v[82:97]
	s_waitcnt lgkmcnt(0)
	v_mfma_f32_32x32x16_bf16 v[82:97], v[72:75], v[110:113], v[82:97]
.LBB0_1259:
	s_cmp_lg_u32 s87, 0
	s_cselect_b64 s[8:9], -1, 0
	s_ashr_i32 s1, s10, 31
	s_add_u32 s0, s68, s10
	s_addc_u32 s1, s69, s1
	s_lshl_b64 s[0:1], s[0:1], 11
	v_lshl_add_u64 v[66:67], v[124:125], 0, s[0:1]
	s_nop 4
	v_cvt_pk_bf16_f32 v68, v82, v83
	global_store_dword v[66:67], v68, off nt
	v_cvt_pk_bf16_f32 v68, v84, v85
	global_store_dword v[66:67], v68, off offset:256 nt
	v_cvt_pk_bf16_f32 v68, v86, v87
	global_store_dword v[66:67], v68, off offset:512 nt
	v_cvt_pk_bf16_f32 v68, v88, v89
	global_store_dword v[66:67], v68, off offset:768 nt
	v_cvt_pk_bf16_f32 v68, v90, v91
	global_store_dword v[66:67], v68, off offset:1024 nt
	v_cvt_pk_bf16_f32 v68, v92, v93
	global_store_dword v[66:67], v68, off offset:1280 nt
	v_cvt_pk_bf16_f32 v68, v94, v95
	global_store_dword v[66:67], v68, off offset:1536 nt
	v_cvt_pk_bf16_f32 v68, v96, v97
	global_store_dword v[66:67], v68, off offset:1792 nt
	v_lshl_or_b32 v66, s50, 5, v156
	v_mul_lo_u32 v66, v66, s86
	v_add3_u32 v66, 0, v66, v126
	ds_read_b128 v[78:81], v66 offset:53248
	ds_read_b128 v[74:77], v66 offset:53280
	ds_read_b128 v[70:73], v66 offset:53312
	ds_read_b128 v[66:69], v66 offset:53344
	s_lshl_b64 s[0:1], s[48:49], 16
	s_add_u32 s10, s77, s0
	s_addc_u32 s11, s78, s1
	s_lshl_b64 s[0:1], s[50:51], 13
	s_add_u32 s0, s10, s0
	s_addc_u32 s1, s11, s1
	v_lshlrev_b32_e32 v114, 1, v127
	v_lshl_add_u64 v[82:83], s[0:1], 0, v[114:115]
	s_and_b64 vcc, exec, s[8:9]
	v_lshlrev_b32_e32 v114, 4, v156
	v_or_b32_e32 v84, 32, v156
	s_cbranch_vccz .LBB0_1268
	v_cvt_pk_bf16_f32 v86, v50, v51
	v_cvt_pk_bf16_f32 v87, v52, v53
	v_lshl_add_u64 v[88:89], v[82:83], 0, v[114:115]
	global_store_dwordx2 v[88:89], v[86:87], off nt
	v_or_b32_e32 v87, 32, v156
	v_lshlrev_b32_e32 v92, 4, v87
	v_mov_b32_e32 v93, v115
	v_cvt_pk_bf16_f32 v90, v54, v55
	v_cvt_pk_bf16_f32 v91, v56, v57
	v_lshl_add_u64 v[92:93], v[82:83], 0, v[92:93]
	global_store_dwordx2 v[92:93], v[90:91], off nt
	v_cvt_pk_bf16_f32 v90, v58, v59
	v_cvt_pk_bf16_f32 v91, v60, v61
	global_store_dwordx2 v[88:89], v[90:91], off offset:1024 nt
	v_cvt_pk_bf16_f32 v88, v62, v63
	v_cvt_pk_bf16_f32 v89, v64, v65
	global_store_dwordx2 v[92:93], v[88:89], off offset:1024 nt
	s_cbranch_execnz .LBB0_1262

.LBB0_1262:
	v_lshl_add_u32 v86, v127, 2, 0
	v_add_u32_e32 v84, 0x18b40, v86
	v_add_u32_e32 v85, 0x18b60, v86
	ds_read_b128 v[88:91], v84
	ds_read_b128 v[92:95], v85
	v_add_u32_e32 v84, 0x18b00, v86
	v_add_u32_e32 v85, 0x18b20, v86
	ds_read_b128 v[96:99], v84
	ds_read_b128 v[100:103], v85
	v_mad_u32_u24 v84, v156, s86, v128
	ds_read_b128 v[104:107], v84 offset:34816
	s_waitcnt lgkmcnt(3)
	v_pk_mul_f32 v[64:65], v[64:65], v[94:95]
	v_pk_mul_f32 v[60:61], v[60:61], v[90:91]
	s_waitcnt lgkmcnt(1)
	v_pk_mul_f32 v[56:57], v[56:57], v[102:103]
	v_pk_mul_f32 v[52:53], v[52:53], v[98:99]
	v_pk_mul_f32 v[62:63], v[62:63], v[92:93]
	v_pk_mul_f32 v[58:59], v[58:59], v[88:89]
	v_pk_mul_f32 v[54:55], v[54:55], v[100:101]
	v_pk_mul_f32 v[50:51], v[50:51], v[96:97]
	ds_read_b128 v[88:91], v84 offset:34848
	s_andn2_b64 vcc, exec, s[8:9]
	s_waitcnt lgkmcnt(1)
	v_mfma_f32_32x32x16_bf16 v[50:65], v[104:107], v[78:81], v[50:65]
	s_waitcnt lgkmcnt(0)
	v_mfma_f32_32x32x16_bf16 v[50:65], v[88:91], v[74:77], v[50:65]
	ds_read_b128 v[88:91], v84 offset:34880
	ds_read_b128 v[92:95], v84 offset:34912
	v_cndmask_b32_e64 v84, 0, 1, s[8:9]
	v_cmp_ne_u32_e64 s[0:1], 1, v84
	v_lshlrev_b32_e32 v84, 4, v87
	s_waitcnt lgkmcnt(1)
	v_mfma_f32_32x32x16_bf16 v[50:65], v[88:91], v[70:73], v[50:65]
	s_waitcnt lgkmcnt(0)
	v_mfma_f32_32x32x16_bf16 v[50:65], v[92:95], v[66:69], v[50:65]
	s_cbranch_vccnz .LBB0_1264
	v_cvt_pk_bf16_f32 v88, v34, v35
	v_cvt_pk_bf16_f32 v89, v36, v37
	v_lshl_add_u64 v[90:91], v[82:83], 0, v[114:115]
	v_mov_b32_e32 v85, v115
	global_store_dwordx2 v[90:91], v[88:89], off offset:2048 nt
	v_cvt_pk_bf16_f32 v88, v38, v39
	v_cvt_pk_bf16_f32 v89, v40, v41
	v_lshl_add_u64 v[92:93], v[82:83], 0, v[84:85]
	global_store_dwordx2 v[92:93], v[88:89], off offset:2048 nt
	v_cvt_pk_bf16_f32 v88, v42, v43
	v_cvt_pk_bf16_f32 v89, v44, v45
	global_store_dwordx2 v[90:91], v[88:89], off offset:3072 nt
	v_cvt_pk_bf16_f32 v88, v46, v47
	v_cvt_pk_bf16_f32 v89, v48, v49
	global_store_dwordx2 v[92:93], v[88:89], off offset:3072 nt
.LBB0_1264:
	v_add_u32_e32 v85, 0x18bc0, v86
	v_add_u32_e32 v92, 0x18be0, v86
	ds_read_b128 v[88:91], v85
	ds_read_b128 v[92:95], v92
	v_add_u32_e32 v85, 0x18b80, v86
	v_add_u32_e32 v100, 0x18ba0, v86
	ds_read_b128 v[96:99], v85
	ds_read_b128 v[100:103], v100
	v_mad_i32_i24 v85, v87, s86, v128
	ds_read_b128 v[104:107], v85 offset:34816
	s_waitcnt lgkmcnt(3)
	v_pk_mul_f32 v[48:49], v[48:49], v[94:95]
	v_pk_mul_f32 v[44:45], v[44:45], v[90:91]
	s_waitcnt lgkmcnt(1)
	v_pk_mul_f32 v[40:41], v[40:41], v[102:103]
	v_pk_mul_f32 v[36:37], v[36:37], v[98:99]
	v_pk_mul_f32 v[46:47], v[46:47], v[92:93]
	v_pk_mul_f32 v[42:43], v[42:43], v[88:89]
	v_pk_mul_f32 v[38:39], v[38:39], v[100:101]
	v_pk_mul_f32 v[34:35], v[34:35], v[96:97]
	ds_read_b128 v[88:91], v85 offset:34848
	s_and_b64 vcc, exec, s[0:1]
	s_waitcnt lgkmcnt(1)
	v_mfma_f32_32x32x16_bf16 v[34:49], v[104:107], v[78:81], v[34:49]
	s_waitcnt lgkmcnt(0)
	v_mfma_f32_32x32x16_bf16 v[34:49], v[88:91], v[74:77], v[34:49]
	ds_read_b128 v[88:91], v85 offset:34880
	ds_read_b128 v[92:95], v85 offset:34912
	s_waitcnt lgkmcnt(1)
	v_mfma_f32_32x32x16_bf16 v[34:49], v[88:91], v[70:73], v[34:49]
	s_waitcnt lgkmcnt(0)
	v_mfma_f32_32x32x16_bf16 v[34:49], v[92:95], v[66:69], v[34:49]
	s_cbranch_vccnz .LBB0_1266
	v_lshl_add_u64 v[90:91], v[82:83], 0, s[38:39]
	v_cvt_pk_bf16_f32 v88, v18, v19
	v_cvt_pk_bf16_f32 v89, v20, v21
	v_lshl_add_u64 v[92:93], v[90:91], 0, v[114:115]
	v_mov_b32_e32 v85, v115
	global_store_dwordx2 v[92:93], v[88:89], off nt
	v_cvt_pk_bf16_f32 v88, v22, v23
	v_cvt_pk_bf16_f32 v89, v24, v25
	v_lshl_add_u64 v[90:91], v[90:91], 0, v[84:85]
	global_store_dwordx2 v[90:91], v[88:89], off nt
	v_lshl_add_u64 v[90:91], v[82:83], 0, s[40:41]
	v_cvt_pk_bf16_f32 v88, v26, v27
	v_cvt_pk_bf16_f32 v89, v28, v29
	v_lshl_add_u64 v[92:93], v[90:91], 0, v[114:115]
	global_store_dwordx2 v[92:93], v[88:89], off nt
	v_cvt_pk_bf16_f32 v88, v30, v31
	v_cvt_pk_bf16_f32 v89, v32, v33
	v_lshl_add_u64 v[90:91], v[90:91], 0, v[84:85]
	global_store_dwordx2 v[90:91], v[88:89], off nt
.LBB0_1266:
	v_add_u32_e32 v87, 0x18c40, v86
	v_add_u32_e32 v92, 0x18c60, v86
	v_mul_u32_u24_e32 v85, 0x90, v156
	ds_read_b128 v[88:91], v87
	ds_read_b128 v[92:95], v92
	v_add_u32_e32 v87, 0x18c00, v86
	v_add_u32_e32 v100, 0x18c20, v86
	ds_read_b128 v[96:99], v87
	ds_read_b128 v[100:103], v100
	v_add_u32_e32 v87, v128, v85
	ds_read_b128 v[104:107], v87 offset:44032
	s_waitcnt lgkmcnt(3)
	v_pk_mul_f32 v[32:33], v[32:33], v[94:95]
	v_pk_mul_f32 v[28:29], v[28:29], v[90:91]
	s_waitcnt lgkmcnt(1)
	v_pk_mul_f32 v[24:25], v[24:25], v[102:103]
	v_pk_mul_f32 v[20:21], v[20:21], v[98:99]
	v_pk_mul_f32 v[30:31], v[30:31], v[92:93]
	v_pk_mul_f32 v[26:27], v[26:27], v[88:89]
	v_pk_mul_f32 v[22:23], v[22:23], v[100:101]
	v_pk_mul_f32 v[18:19], v[18:19], v[96:97]
	ds_read_b128 v[88:91], v87 offset:44064
	s_and_b64 vcc, exec, s[0:1]
	s_waitcnt lgkmcnt(1)
	v_mfma_f32_32x32x16_bf16 v[18:33], v[104:107], v[78:81], v[18:33]
	s_waitcnt lgkmcnt(0)
	v_mfma_f32_32x32x16_bf16 v[18:33], v[88:91], v[74:77], v[18:33]
	ds_read_b128 v[88:91], v87 offset:44096
	ds_read_b128 v[92:95], v87 offset:44128
	s_waitcnt lgkmcnt(1)
	v_mfma_f32_32x32x16_bf16 v[18:33], v[88:91], v[70:73], v[18:33]
	s_waitcnt lgkmcnt(0)
	v_mfma_f32_32x32x16_bf16 v[18:33], v[92:95], v[66:69], v[18:33]
	s_cbranch_vccnz .LBB0_1089
	v_lshl_add_u64 v[90:91], v[82:83], 0, s[42:43]
	v_cvt_pk_bf16_f32 v88, v2, v3
	v_cvt_pk_bf16_f32 v89, v4, v5
	v_lshl_add_u64 v[92:93], v[90:91], 0, v[114:115]
	v_mov_b32_e32 v85, v115
	global_store_dwordx2 v[92:93], v[88:89], off nt
	v_cvt_pk_bf16_f32 v88, v6, v7
	v_cvt_pk_bf16_f32 v89, v8, v9
	v_lshl_add_u64 v[90:91], v[90:91], 0, v[84:85]
	v_lshl_add_u64 v[82:83], v[82:83], 0, s[46:47]
	global_store_dwordx2 v[90:91], v[88:89], off nt
	v_cvt_pk_bf16_f32 v88, v10, v11
	v_cvt_pk_bf16_f32 v89, v12, v13
	v_lshl_add_u64 v[90:91], v[82:83], 0, v[114:115]
	global_store_dwordx2 v[90:91], v[88:89], off nt
	v_cvt_pk_bf16_f32 v88, v14, v15
	v_cvt_pk_bf16_f32 v89, v16, v17
	v_lshl_add_u64 v[82:83], v[82:83], 0, v[84:85]
	global_store_dwordx2 v[82:83], v[88:89], off nt
	s_branch .LBB0_1089
